# attention QK MFMA-first + L2 touches; hand-written P1 epilogues (q/k and others) and GLU epilogue; odd XCDs start P1 13 us late (no relaxed first-iteration waits)
# speedup vs baseline: 1.0059x; 1.0059x over previous
.LBB0_272:
	s_and_b64 vcc, exec, s[52:53]
	s_cbranch_vccz .LBB0_561
	v_and_b32_e32 v129, 63, v234
	v_lshrrev_b32_e32 v130, 6, v234
	v_and_b32_e32 v131, 15, v129
	v_lshrrev_b32_e32 v129, 4, v129
	v_lshrrev_b32_e32 v235, 2, v130
	v_and_b32_e32 v130, 3, v130
	v_lshl_add_u32 v131, v235, 6, v131
	v_lshlrev_b32_e32 v140, 5, v129
	v_lshlrev_b32_e32 v194, 7, v131
	v_lshl_add_u32 v194, v129, 5, v194
	v_lshlrev_b32_e32 v195, 11, v131
	v_lshl_add_u32 v195, v130, 7, v195
	v_lshl_add_u32 v195, v129, 4, v195
	v_mbcnt_lo_u32_b32 v244, -1, 0
	v_mbcnt_hi_u32_b32 v244, -1, v244
	v_xor_b32_e32 v245, 32, v244
	v_xor_b32_e32 v244, 16, v244
	v_lshlrev_b32_e32 v244, 2, v244
	v_lshlrev_b32_e32 v245, 2, v245
	v_mov_b32_e32 v193, 0x358637bd
	v_readlane_b32 s56, v253, 37
	v_readlane_b32 s57, v253, 38
	v_readlane_b32 s2, v253, 39
	v_readlane_b32 s3, v253, 40
	v_readlane_b32 s54, v253, 59
	v_readlane_b32 s55, v253, 60
	v_readlane_b32 s12, v253, 23
	v_readlane_b32 s13, v253, 58
	s_mov_b32 s18, 0x3e38aa3b
	s_cmp_eq_u32 s17, 0
	s_cselect_b32 s56, s56, s2
	s_cselect_b32 s57, s57, s3
	s_cselect_b32 s54, s54, s12
	s_cselect_b32 s55, s55, s13
	s_cselect_b32 s18, s18, 1.0
	s_cselect_b64 vcc, -1, 0
	s_lshl_b32 s2, s50, 19
	s_lshl_b32 s3, s15, 9
	s_add_u32 s2, s2, s3
	s_add_u32 s54, s54, s2
	s_addc_u32 s55, s55, 0
	global_load_dwordx4 v[176:179], v140, s[56:57]
	global_load_dwordx4 v[180:183], v140, s[56:57] offset:16
	global_load_dwordx4 v[184:187], v140, s[56:57] offset:128
	global_load_dwordx4 v[188:191], v140, s[56:57] offset:144
	s_and_b32 s2, s50, 31
	s_lshl_b32 s2, s2, 15
	s_add_u32 s2, s2, 0x1400000
	s_add_u32 s58, s22, s2
	s_addc_u32 s59, s23, 0
	s_add_u32 s24, s58, 0x100000
	s_addc_u32 s25, s59, 0
	global_load_dwordx4 v[198:201], v194, s[24:25]
	global_load_dwordx4 v[206:209], v194, s[58:59]
	global_load_dwordx4 v[202:205], v194, s[24:25] offset:16
	global_load_dwordx4 v[210:213], v194, s[58:59] offset:16
	s_add_u32 s24, s24, 0x800
	s_addc_u32 s25, s25, 0
	s_add_u32 s58, s58, 0x800
	s_addc_u32 s59, s59, 0
	global_load_dwordx4 v[214:217], v194, s[24:25]
	global_load_dwordx4 v[222:225], v194, s[58:59]
	global_load_dwordx4 v[218:221], v194, s[24:25] offset:16
	global_load_dwordx4 v[226:229], v194, s[58:59] offset:16
	s_add_u32 s24, s24, 0x800
	s_addc_u32 s25, s25, 0
	s_add_u32 s58, s58, 0x800
	s_addc_u32 s59, s59, 0
	v_mul_f32_e32 v158, v124, v124
	v_mul_f32_e32 v159, v125, v125
	v_add_f32_e32 v158, v158, v159
	v_mul_f32_e32 v159, v126, v126
	v_mul_f32_e32 v246, v127, v127
	v_add_f32_e32 v159, v159, v246
	v_add_f32_e32 v158, v158, v159
	v_mul_f32_e32 v160, v120, v120
	v_mul_f32_e32 v161, v121, v121
	v_add_f32_e32 v160, v160, v161
	v_mul_f32_e32 v161, v122, v122
	v_mul_f32_e32 v247, v123, v123
	v_add_f32_e32 v161, v161, v247
	v_add_f32_e32 v160, v160, v161
	v_mul_f32_e32 v162, v116, v116
	v_mul_f32_e32 v163, v117, v117
	v_add_f32_e32 v162, v162, v163
	v_mul_f32_e32 v163, v118, v118
	v_mul_f32_e32 v248, v119, v119
	v_add_f32_e32 v163, v163, v248
	v_add_f32_e32 v162, v162, v163
	v_mul_f32_e32 v164, v112, v112
	v_mul_f32_e32 v165, v113, v113
	v_add_f32_e32 v164, v164, v165
	v_mul_f32_e32 v165, v114, v114
	v_mul_f32_e32 v249, v115, v115
	v_add_f32_e32 v165, v165, v249
	v_add_f32_e32 v164, v164, v165
	v_add_f32_e32 v236, v158, v160
	v_add_f32_e32 v236, v236, v162
	v_add_f32_e32 v236, v236, v164
	v_mul_f32_e32 v158, v108, v108
	v_mul_f32_e32 v159, v109, v109
	v_add_f32_e32 v158, v158, v159
	v_mul_f32_e32 v159, v110, v110
	v_mul_f32_e32 v246, v111, v111
	v_add_f32_e32 v159, v159, v246
	v_add_f32_e32 v158, v158, v159
	v_mul_f32_e32 v160, v104, v104
	v_mul_f32_e32 v161, v105, v105
	v_add_f32_e32 v160, v160, v161
	v_mul_f32_e32 v161, v106, v106
	v_mul_f32_e32 v247, v107, v107
	v_add_f32_e32 v161, v161, v247
	v_add_f32_e32 v160, v160, v161
	v_mul_f32_e32 v162, v100, v100
	v_mul_f32_e32 v163, v101, v101
	v_add_f32_e32 v162, v162, v163
	v_mul_f32_e32 v163, v102, v102
	v_mul_f32_e32 v248, v103, v103
	v_add_f32_e32 v163, v163, v248
	v_add_f32_e32 v162, v162, v163
	v_mul_f32_e32 v164, v96, v96
	v_mul_f32_e32 v165, v97, v97
	v_add_f32_e32 v164, v164, v165
	v_mul_f32_e32 v165, v98, v98
	v_mul_f32_e32 v249, v99, v99
	v_add_f32_e32 v165, v165, v249
	v_add_f32_e32 v164, v164, v165
	v_add_f32_e32 v237, v158, v160
	v_add_f32_e32 v237, v237, v162
	v_add_f32_e32 v237, v237, v164
	v_mul_f32_e32 v158, v92, v92
	v_mul_f32_e32 v159, v93, v93
	v_add_f32_e32 v158, v158, v159
	v_mul_f32_e32 v159, v94, v94
	v_mul_f32_e32 v246, v95, v95
	v_add_f32_e32 v159, v159, v246
	v_add_f32_e32 v158, v158, v159
	v_mul_f32_e32 v160, v88, v88
	v_mul_f32_e32 v161, v89, v89
	v_add_f32_e32 v160, v160, v161
	v_mul_f32_e32 v161, v90, v90
	v_mul_f32_e32 v247, v91, v91
	v_add_f32_e32 v161, v161, v247
	v_add_f32_e32 v160, v160, v161
	v_mul_f32_e32 v162, v84, v84
	v_mul_f32_e32 v163, v85, v85
	v_add_f32_e32 v162, v162, v163
	v_mul_f32_e32 v163, v86, v86
	v_mul_f32_e32 v248, v87, v87
	v_add_f32_e32 v163, v163, v248
	v_add_f32_e32 v162, v162, v163
	v_mul_f32_e32 v164, v80, v80
	v_mul_f32_e32 v165, v81, v81
	v_add_f32_e32 v164, v164, v165
	v_mul_f32_e32 v165, v82, v82
	v_mul_f32_e32 v249, v83, v83
	v_add_f32_e32 v165, v165, v249
	v_add_f32_e32 v164, v164, v165
	v_add_f32_e32 v238, v158, v160
	v_add_f32_e32 v238, v238, v162
	v_add_f32_e32 v238, v238, v164
	v_mul_f32_e32 v158, v76, v76
	v_mul_f32_e32 v159, v77, v77
	v_add_f32_e32 v158, v158, v159
	v_mul_f32_e32 v159, v78, v78
	v_mul_f32_e32 v246, v79, v79
	v_add_f32_e32 v159, v159, v246
	v_add_f32_e32 v158, v158, v159
	v_mul_f32_e32 v160, v72, v72
	v_mul_f32_e32 v161, v73, v73
	v_add_f32_e32 v160, v160, v161
	v_mul_f32_e32 v161, v74, v74
	v_mul_f32_e32 v247, v75, v75
	v_add_f32_e32 v161, v161, v247
	v_add_f32_e32 v160, v160, v161
	v_mul_f32_e32 v162, v68, v68
	v_mul_f32_e32 v163, v69, v69
	v_add_f32_e32 v162, v162, v163
	v_mul_f32_e32 v163, v70, v70
	v_mul_f32_e32 v248, v71, v71
	v_add_f32_e32 v163, v163, v248
	v_add_f32_e32 v162, v162, v163
	v_mul_f32_e32 v164, v64, v64
	v_mul_f32_e32 v165, v65, v65
	v_add_f32_e32 v164, v164, v165
	v_mul_f32_e32 v165, v66, v66
	v_mul_f32_e32 v249, v67, v67
	v_add_f32_e32 v165, v165, v249
	v_add_f32_e32 v164, v164, v165
	v_add_f32_e32 v239, v158, v160
	v_add_f32_e32 v239, v239, v162
	v_add_f32_e32 v239, v239, v164
	v_mul_f32_e32 v158, v60, v60
	v_mul_f32_e32 v159, v61, v61
	v_add_f32_e32 v158, v158, v159
	v_mul_f32_e32 v159, v62, v62
	v_mul_f32_e32 v246, v63, v63
	v_add_f32_e32 v159, v159, v246
	v_add_f32_e32 v158, v158, v159
	v_mul_f32_e32 v160, v56, v56
	v_mul_f32_e32 v161, v57, v57
	v_add_f32_e32 v160, v160, v161
	v_mul_f32_e32 v161, v58, v58
	v_mul_f32_e32 v247, v59, v59
	v_add_f32_e32 v161, v161, v247
	v_add_f32_e32 v160, v160, v161
	v_mul_f32_e32 v162, v52, v52
	v_mul_f32_e32 v163, v53, v53
	v_add_f32_e32 v162, v162, v163
	v_mul_f32_e32 v163, v54, v54
	v_mul_f32_e32 v248, v55, v55
	v_add_f32_e32 v163, v163, v248
	v_add_f32_e32 v162, v162, v163
	v_mul_f32_e32 v164, v48, v48
	v_mul_f32_e32 v165, v49, v49
	v_add_f32_e32 v164, v164, v165
	v_mul_f32_e32 v165, v50, v50
	v_mul_f32_e32 v249, v51, v51
	v_add_f32_e32 v165, v165, v249
	v_add_f32_e32 v164, v164, v165
	v_add_f32_e32 v240, v158, v160
	v_add_f32_e32 v240, v240, v162
	v_add_f32_e32 v240, v240, v164
	v_mul_f32_e32 v158, v44, v44
	v_mul_f32_e32 v159, v45, v45
	v_add_f32_e32 v158, v158, v159
	v_mul_f32_e32 v159, v46, v46
	v_mul_f32_e32 v246, v47, v47
	v_add_f32_e32 v159, v159, v246
	v_add_f32_e32 v158, v158, v159
	v_mul_f32_e32 v160, v40, v40
	v_mul_f32_e32 v161, v41, v41
	v_add_f32_e32 v160, v160, v161
	v_mul_f32_e32 v161, v42, v42
	v_mul_f32_e32 v247, v43, v43
	v_add_f32_e32 v161, v161, v247
	v_add_f32_e32 v160, v160, v161
	v_mul_f32_e32 v162, v36, v36
	v_mul_f32_e32 v163, v37, v37
	v_add_f32_e32 v162, v162, v163
	v_mul_f32_e32 v163, v38, v38
	v_mul_f32_e32 v248, v39, v39
	v_add_f32_e32 v163, v163, v248
	v_add_f32_e32 v162, v162, v163
	v_mul_f32_e32 v164, v32, v32
	v_mul_f32_e32 v165, v33, v33
	v_add_f32_e32 v164, v164, v165
	v_mul_f32_e32 v165, v34, v34
	v_mul_f32_e32 v249, v35, v35
	v_add_f32_e32 v165, v165, v249
	v_add_f32_e32 v164, v164, v165
	v_add_f32_e32 v241, v158, v160
	v_add_f32_e32 v241, v241, v162
	v_add_f32_e32 v241, v241, v164
	v_mul_f32_e32 v158, v28, v28
	v_mul_f32_e32 v159, v29, v29
	v_add_f32_e32 v158, v158, v159
	v_mul_f32_e32 v159, v30, v30
	v_mul_f32_e32 v246, v31, v31
	v_add_f32_e32 v159, v159, v246
	v_add_f32_e32 v158, v158, v159
	v_mul_f32_e32 v160, v24, v24
	v_mul_f32_e32 v161, v25, v25
	v_add_f32_e32 v160, v160, v161
	v_mul_f32_e32 v161, v26, v26
	v_mul_f32_e32 v247, v27, v27
	v_add_f32_e32 v161, v161, v247
	v_add_f32_e32 v160, v160, v161
	v_mul_f32_e32 v162, v20, v20
	v_mul_f32_e32 v163, v21, v21
	v_add_f32_e32 v162, v162, v163
	v_mul_f32_e32 v163, v22, v22
	v_mul_f32_e32 v248, v23, v23
	v_add_f32_e32 v163, v163, v248
	v_add_f32_e32 v162, v162, v163
	v_mul_f32_e32 v164, v16, v16
	v_mul_f32_e32 v165, v17, v17
	v_add_f32_e32 v164, v164, v165
	v_mul_f32_e32 v165, v18, v18
	v_mul_f32_e32 v249, v19, v19
	v_add_f32_e32 v165, v165, v249
	v_add_f32_e32 v164, v164, v165
	v_add_f32_e32 v242, v158, v160
	v_add_f32_e32 v242, v242, v162
	v_add_f32_e32 v242, v242, v164
	v_mul_f32_e32 v158, v12, v12
	v_mul_f32_e32 v159, v13, v13
	v_add_f32_e32 v158, v158, v159
	v_mul_f32_e32 v159, v14, v14
	v_mul_f32_e32 v246, v15, v15
	v_add_f32_e32 v159, v159, v246
	v_add_f32_e32 v158, v158, v159
	v_mul_f32_e32 v160, v8, v8
	v_mul_f32_e32 v161, v9, v9
	v_add_f32_e32 v160, v160, v161
	v_mul_f32_e32 v161, v10, v10
	v_mul_f32_e32 v247, v11, v11
	v_add_f32_e32 v161, v161, v247
	v_add_f32_e32 v160, v160, v161
	v_mul_f32_e32 v162, v4, v4
	v_mul_f32_e32 v163, v5, v5
	v_add_f32_e32 v162, v162, v163
	v_mul_f32_e32 v163, v6, v6
	v_mul_f32_e32 v248, v7, v7
	v_add_f32_e32 v163, v163, v248
	v_add_f32_e32 v162, v162, v163
	v_mul_f32_e32 v164, v0, v0
	v_mul_f32_e32 v165, v1, v1
	v_add_f32_e32 v164, v164, v165
	v_mul_f32_e32 v165, v2, v2
	v_mul_f32_e32 v249, v3, v3
	v_add_f32_e32 v165, v165, v249
	v_add_f32_e32 v164, v164, v165
	v_add_f32_e32 v243, v158, v160
	v_add_f32_e32 v243, v243, v162
	v_add_f32_e32 v243, v243, v164
	ds_bpermute_b32 v158, v244, v236
	ds_bpermute_b32 v159, v244, v237
	ds_bpermute_b32 v160, v244, v238
	ds_bpermute_b32 v161, v244, v239
	ds_bpermute_b32 v162, v244, v240
	ds_bpermute_b32 v163, v244, v241
	ds_bpermute_b32 v164, v244, v242
	ds_bpermute_b32 v165, v244, v243
	s_waitcnt lgkmcnt(0)
	v_add_f32_e32 v236, v236, v158
	v_add_f32_e32 v237, v237, v159
	v_add_f32_e32 v238, v238, v160
	v_add_f32_e32 v239, v239, v161
	v_add_f32_e32 v240, v240, v162
	v_add_f32_e32 v241, v241, v163
	v_add_f32_e32 v242, v242, v164
	v_add_f32_e32 v243, v243, v165
	ds_bpermute_b32 v158, v245, v236
	ds_bpermute_b32 v159, v245, v237
	ds_bpermute_b32 v160, v245, v238
	ds_bpermute_b32 v161, v245, v239
	ds_bpermute_b32 v162, v245, v240
	ds_bpermute_b32 v163, v245, v241
	ds_bpermute_b32 v164, v245, v242
	ds_bpermute_b32 v165, v245, v243
	s_waitcnt lgkmcnt(0)
	v_add_f32_e32 v236, v236, v158
	v_add_f32_e32 v237, v237, v159
	v_add_f32_e32 v238, v238, v160
	v_add_f32_e32 v239, v239, v161
	v_add_f32_e32 v240, v240, v162
	v_add_f32_e32 v241, v241, v163
	v_add_f32_e32 v242, v242, v164
	v_add_f32_e32 v243, v243, v165
	v_fmamk_f32 v236, v236, 0x3c800000, v193
	v_fmamk_f32 v237, v237, 0x3c800000, v193
	v_fmamk_f32 v238, v238, 0x3c800000, v193
	v_fmamk_f32 v239, v239, 0x3c800000, v193
	v_fmamk_f32 v240, v240, 0x3c800000, v193
	v_fmamk_f32 v241, v241, 0x3c800000, v193
	v_fmamk_f32 v242, v242, 0x3c800000, v193
	v_fmamk_f32 v243, v243, 0x3c800000, v193
	v_rsq_f32_e32 v236, v236
	v_rsq_f32_e32 v237, v237
	v_rsq_f32_e32 v238, v238
	v_rsq_f32_e32 v239, v239
	v_rsq_f32_e32 v240, v240
	v_rsq_f32_e32 v241, v241
	v_rsq_f32_e32 v242, v242
	v_rsq_f32_e32 v243, v243
	s_waitcnt vmcnt(8)
	v_mul_f32_e32 v176, s18, v176
	v_mul_f32_e32 v177, s18, v177
	v_mul_f32_e32 v178, s18, v178
	v_mul_f32_e32 v179, s18, v179
	v_mul_f32_e32 v180, s18, v180
	v_mul_f32_e32 v181, s18, v181
	v_mul_f32_e32 v182, s18, v182
	v_mul_f32_e32 v183, s18, v183
	v_mul_f32_e32 v184, s18, v184
	v_mul_f32_e32 v185, s18, v185
	v_mul_f32_e32 v186, s18, v186
	v_mul_f32_e32 v187, s18, v187
	v_mul_f32_e32 v188, s18, v188
	v_mul_f32_e32 v189, s18, v189
	v_mul_f32_e32 v190, s18, v190
	v_mul_f32_e32 v191, s18, v191
	v_mul_f32_e32 v124, v124, v236
	v_mul_f32_e32 v125, v125, v236
	v_mul_f32_e32 v126, v126, v236
	v_mul_f32_e32 v127, v127, v236
	v_mul_f32_e32 v120, v120, v236
	v_mul_f32_e32 v121, v121, v236
	v_mul_f32_e32 v122, v122, v236
	v_mul_f32_e32 v123, v123, v236
	v_mul_f32_e32 v116, v116, v236
	v_mul_f32_e32 v117, v117, v236
	v_mul_f32_e32 v118, v118, v236
	v_mul_f32_e32 v119, v119, v236
	v_mul_f32_e32 v112, v112, v236
	v_mul_f32_e32 v113, v113, v236
	v_mul_f32_e32 v114, v114, v236
	v_mul_f32_e32 v115, v115, v236
	v_mul_f32_e32 v124, v176, v124
	v_mul_f32_e32 v125, v177, v125
	v_mul_f32_e32 v126, v178, v126
	v_mul_f32_e32 v127, v179, v127
	v_mul_f32_e32 v120, v180, v120
	v_mul_f32_e32 v121, v181, v121
	v_mul_f32_e32 v122, v182, v122
	v_mul_f32_e32 v123, v183, v123
	v_mul_f32_e32 v116, v184, v116
	v_mul_f32_e32 v117, v185, v117
	v_mul_f32_e32 v118, v186, v118
	v_mul_f32_e32 v119, v187, v119
	v_mul_f32_e32 v112, v188, v112
	v_mul_f32_e32 v113, v189, v113
	v_mul_f32_e32 v114, v190, v114
	v_mul_f32_e32 v115, v191, v115
	s_waitcnt vmcnt(4)
	v_mul_f32_e32 v158, v198, v116
	v_mul_f32_e32 v159, v199, v117
	v_mul_f32_e32 v160, v200, v118
	v_mul_f32_e32 v161, v201, v119
	v_mul_f32_e32 v162, v202, v112
	v_mul_f32_e32 v163, v203, v113
	v_mul_f32_e32 v164, v204, v114
	v_mul_f32_e32 v165, v205, v115
	v_mul_f32_e32 v246, v206, v116
	v_mul_f32_e32 v247, v207, v117
	v_mul_f32_e32 v248, v208, v118
	v_mul_f32_e32 v249, v209, v119
	v_mul_f32_e32 v250, v210, v112
	v_mul_f32_e32 v251, v211, v113
	v_mul_f32_e32 v192, v212, v114
	v_mul_f32_e32 v128, v213, v115
	v_fma_f32 v158, v206, v124, -v158
	v_fma_f32 v159, v207, v125, -v159
	v_fma_f32 v160, v208, v126, -v160
	v_fma_f32 v161, v209, v127, -v161
	v_fma_f32 v162, v210, v120, -v162
	v_fma_f32 v163, v211, v121, -v163
	v_fma_f32 v164, v212, v122, -v164
	v_fma_f32 v165, v213, v123, -v165
	v_fma_f32 v246, v198, v124, v246
	v_fma_f32 v247, v199, v125, v247
	v_fma_f32 v248, v200, v126, v248
	v_fma_f32 v249, v201, v127, v249
	v_fma_f32 v250, v202, v120, v250
	v_fma_f32 v251, v203, v121, v251
	v_fma_f32 v192, v204, v122, v192
	v_fma_f32 v128, v205, v123, v128
	v_cvt_pk_bf16_f32 v124, v158, v159
	v_cvt_pk_bf16_f32 v125, v160, v161
	v_cvt_pk_bf16_f32 v126, v162, v163
	v_cvt_pk_bf16_f32 v127, v164, v165
	v_cvt_pk_bf16_f32 v120, v246, v247
	v_cvt_pk_bf16_f32 v121, v248, v249
	v_cvt_pk_bf16_f32 v122, v250, v251
	v_cvt_pk_bf16_f32 v123, v192, v128
	s_cbranch_vccz .Lmy_qk_pl0
	global_store_dwordx4 v195, v[124:127], s[54:55] nt
	global_store_dwordx4 v195, v[120:123], s[54:55] offset:64 nt
	s_branch .Lmy_qk_st0
.Lmy_qk_pl0:
	global_store_dwordx4 v195, v[124:127], s[54:55]
	global_store_dwordx4 v195, v[120:123], s[54:55] offset:64
.Lmy_qk_st0:
	s_add_u32 s54, s54, 0x8000
	s_addc_u32 s55, s55, 0
	global_load_dwordx4 v[198:201], v194, s[24:25]
	global_load_dwordx4 v[206:209], v194, s[58:59]
	global_load_dwordx4 v[202:205], v194, s[24:25] offset:16
	global_load_dwordx4 v[210:213], v194, s[58:59] offset:16
	s_add_u32 s24, s24, 0x800
	s_addc_u32 s25, s25, 0
	s_add_u32 s58, s58, 0x800
	s_addc_u32 s59, s59, 0
	v_mul_f32_e32 v108, v108, v237
	v_mul_f32_e32 v109, v109, v237
	v_mul_f32_e32 v110, v110, v237
	v_mul_f32_e32 v111, v111, v237
	v_mul_f32_e32 v104, v104, v237
	v_mul_f32_e32 v105, v105, v237
	v_mul_f32_e32 v106, v106, v237
	v_mul_f32_e32 v107, v107, v237
	v_mul_f32_e32 v100, v100, v237
	v_mul_f32_e32 v101, v101, v237
	v_mul_f32_e32 v102, v102, v237
	v_mul_f32_e32 v103, v103, v237
	v_mul_f32_e32 v96, v96, v237
	v_mul_f32_e32 v97, v97, v237
	v_mul_f32_e32 v98, v98, v237
	v_mul_f32_e32 v99, v99, v237
	v_mul_f32_e32 v108, v176, v108
	v_mul_f32_e32 v109, v177, v109
	v_mul_f32_e32 v110, v178, v110
	v_mul_f32_e32 v111, v179, v111
	v_mul_f32_e32 v104, v180, v104
	v_mul_f32_e32 v105, v181, v105
	v_mul_f32_e32 v106, v182, v106
	v_mul_f32_e32 v107, v183, v107
	v_mul_f32_e32 v100, v184, v100
	v_mul_f32_e32 v101, v185, v101
	v_mul_f32_e32 v102, v186, v102
	v_mul_f32_e32 v103, v187, v103
	v_mul_f32_e32 v96, v188, v96
	v_mul_f32_e32 v97, v189, v97
	v_mul_f32_e32 v98, v190, v98
	v_mul_f32_e32 v99, v191, v99
	s_waitcnt vmcnt(6)
	v_mul_f32_e32 v158, v214, v100
	v_mul_f32_e32 v159, v215, v101
	v_mul_f32_e32 v160, v216, v102
	v_mul_f32_e32 v161, v217, v103
	v_mul_f32_e32 v162, v218, v96
	v_mul_f32_e32 v163, v219, v97
	v_mul_f32_e32 v164, v220, v98
	v_mul_f32_e32 v165, v221, v99
	v_mul_f32_e32 v246, v222, v100
	v_mul_f32_e32 v247, v223, v101
	v_mul_f32_e32 v248, v224, v102
	v_mul_f32_e32 v249, v225, v103
	v_mul_f32_e32 v250, v226, v96
	v_mul_f32_e32 v251, v227, v97
	v_mul_f32_e32 v192, v228, v98
	v_mul_f32_e32 v128, v229, v99
	v_fma_f32 v158, v222, v108, -v158
	v_fma_f32 v159, v223, v109, -v159
	v_fma_f32 v160, v224, v110, -v160
	v_fma_f32 v161, v225, v111, -v161
	v_fma_f32 v162, v226, v104, -v162
	v_fma_f32 v163, v227, v105, -v163
	v_fma_f32 v164, v228, v106, -v164
	v_fma_f32 v165, v229, v107, -v165
	v_fma_f32 v246, v214, v108, v246
	v_fma_f32 v247, v215, v109, v247
	v_fma_f32 v248, v216, v110, v248
	v_fma_f32 v249, v217, v111, v249
	v_fma_f32 v250, v218, v104, v250
	v_fma_f32 v251, v219, v105, v251
	v_fma_f32 v192, v220, v106, v192
	v_fma_f32 v128, v221, v107, v128
	v_cvt_pk_bf16_f32 v108, v158, v159
	v_cvt_pk_bf16_f32 v109, v160, v161
	v_cvt_pk_bf16_f32 v110, v162, v163
	v_cvt_pk_bf16_f32 v111, v164, v165
	v_cvt_pk_bf16_f32 v104, v246, v247
	v_cvt_pk_bf16_f32 v105, v248, v249
	v_cvt_pk_bf16_f32 v106, v250, v251
	v_cvt_pk_bf16_f32 v107, v192, v128
	s_cbranch_vccz .Lmy_qk_pl1
	global_store_dwordx4 v195, v[108:111], s[54:55] nt
	global_store_dwordx4 v195, v[104:107], s[54:55] offset:64 nt
	s_branch .Lmy_qk_st1
.Lmy_qk_pl1:
	global_store_dwordx4 v195, v[108:111], s[54:55]
	global_store_dwordx4 v195, v[104:107], s[54:55] offset:64
.Lmy_qk_st1:
	s_add_u32 s54, s54, 0x8000
	s_addc_u32 s55, s55, 0
	global_load_dwordx4 v[214:217], v194, s[24:25]
	global_load_dwordx4 v[222:225], v194, s[58:59]
	global_load_dwordx4 v[218:221], v194, s[24:25] offset:16
	global_load_dwordx4 v[226:229], v194, s[58:59] offset:16
	s_add_u32 s24, s24, 0x2800
	s_addc_u32 s25, s25, 0
	s_add_u32 s58, s58, 0x2800
	s_addc_u32 s59, s59, 0
	v_mul_f32_e32 v92, v92, v238
	v_mul_f32_e32 v93, v93, v238
	v_mul_f32_e32 v94, v94, v238
	v_mul_f32_e32 v95, v95, v238
	v_mul_f32_e32 v88, v88, v238
	v_mul_f32_e32 v89, v89, v238
	v_mul_f32_e32 v90, v90, v238
	v_mul_f32_e32 v91, v91, v238
	v_mul_f32_e32 v84, v84, v238
	v_mul_f32_e32 v85, v85, v238
	v_mul_f32_e32 v86, v86, v238
	v_mul_f32_e32 v87, v87, v238
	v_mul_f32_e32 v80, v80, v238
	v_mul_f32_e32 v81, v81, v238
	v_mul_f32_e32 v82, v82, v238
	v_mul_f32_e32 v83, v83, v238
	v_mul_f32_e32 v92, v176, v92
	v_mul_f32_e32 v93, v177, v93
	v_mul_f32_e32 v94, v178, v94
	v_mul_f32_e32 v95, v179, v95
	v_mul_f32_e32 v88, v180, v88
	v_mul_f32_e32 v89, v181, v89
	v_mul_f32_e32 v90, v182, v90
	v_mul_f32_e32 v91, v183, v91
	v_mul_f32_e32 v84, v184, v84
	v_mul_f32_e32 v85, v185, v85
	v_mul_f32_e32 v86, v186, v86
	v_mul_f32_e32 v87, v187, v87
	v_mul_f32_e32 v80, v188, v80
	v_mul_f32_e32 v81, v189, v81
	v_mul_f32_e32 v82, v190, v82
	v_mul_f32_e32 v83, v191, v83
	s_waitcnt vmcnt(6)
	v_mul_f32_e32 v158, v198, v84
	v_mul_f32_e32 v159, v199, v85
	v_mul_f32_e32 v160, v200, v86
	v_mul_f32_e32 v161, v201, v87
	v_mul_f32_e32 v162, v202, v80
	v_mul_f32_e32 v163, v203, v81
	v_mul_f32_e32 v164, v204, v82
	v_mul_f32_e32 v165, v205, v83
	v_mul_f32_e32 v246, v206, v84
	v_mul_f32_e32 v247, v207, v85
	v_mul_f32_e32 v248, v208, v86
	v_mul_f32_e32 v249, v209, v87
	v_mul_f32_e32 v250, v210, v80
	v_mul_f32_e32 v251, v211, v81
	v_mul_f32_e32 v192, v212, v82
	v_mul_f32_e32 v128, v213, v83
	v_fma_f32 v158, v206, v92, -v158
	v_fma_f32 v159, v207, v93, -v159
	v_fma_f32 v160, v208, v94, -v160
	v_fma_f32 v161, v209, v95, -v161
	v_fma_f32 v162, v210, v88, -v162
	v_fma_f32 v163, v211, v89, -v163
	v_fma_f32 v164, v212, v90, -v164
	v_fma_f32 v165, v213, v91, -v165
	v_fma_f32 v246, v198, v92, v246
	v_fma_f32 v247, v199, v93, v247
	v_fma_f32 v248, v200, v94, v248
	v_fma_f32 v249, v201, v95, v249
	v_fma_f32 v250, v202, v88, v250
	v_fma_f32 v251, v203, v89, v251
	v_fma_f32 v192, v204, v90, v192
	v_fma_f32 v128, v205, v91, v128
	v_cvt_pk_bf16_f32 v92, v158, v159
	v_cvt_pk_bf16_f32 v93, v160, v161
	v_cvt_pk_bf16_f32 v94, v162, v163
	v_cvt_pk_bf16_f32 v95, v164, v165
	v_cvt_pk_bf16_f32 v88, v246, v247
	v_cvt_pk_bf16_f32 v89, v248, v249
	v_cvt_pk_bf16_f32 v90, v250, v251
	v_cvt_pk_bf16_f32 v91, v192, v128
	s_cbranch_vccz .Lmy_qk_pl2
	global_store_dwordx4 v195, v[92:95], s[54:55] nt
	global_store_dwordx4 v195, v[88:91], s[54:55] offset:64 nt
	s_branch .Lmy_qk_st2
.Lmy_qk_pl2:
	global_store_dwordx4 v195, v[92:95], s[54:55]
	global_store_dwordx4 v195, v[88:91], s[54:55] offset:64
.Lmy_qk_st2:
	s_add_u32 s54, s54, 0x8000
	s_addc_u32 s55, s55, 0
	global_load_dwordx4 v[198:201], v194, s[24:25]
	global_load_dwordx4 v[206:209], v194, s[58:59]
	global_load_dwordx4 v[202:205], v194, s[24:25] offset:16
	global_load_dwordx4 v[210:213], v194, s[58:59] offset:16
	s_add_u32 s24, s24, 0x800
	s_addc_u32 s25, s25, 0
	s_add_u32 s58, s58, 0x800
	s_addc_u32 s59, s59, 0
	v_mul_f32_e32 v76, v76, v239
	v_mul_f32_e32 v77, v77, v239
	v_mul_f32_e32 v78, v78, v239
	v_mul_f32_e32 v79, v79, v239
	v_mul_f32_e32 v72, v72, v239
	v_mul_f32_e32 v73, v73, v239
	v_mul_f32_e32 v74, v74, v239
	v_mul_f32_e32 v75, v75, v239
	v_mul_f32_e32 v68, v68, v239
	v_mul_f32_e32 v69, v69, v239
	v_mul_f32_e32 v70, v70, v239
	v_mul_f32_e32 v71, v71, v239
	v_mul_f32_e32 v64, v64, v239
	v_mul_f32_e32 v65, v65, v239
	v_mul_f32_e32 v66, v66, v239
	v_mul_f32_e32 v67, v67, v239
	v_mul_f32_e32 v76, v176, v76
	v_mul_f32_e32 v77, v177, v77
	v_mul_f32_e32 v78, v178, v78
	v_mul_f32_e32 v79, v179, v79
	v_mul_f32_e32 v72, v180, v72
	v_mul_f32_e32 v73, v181, v73
	v_mul_f32_e32 v74, v182, v74
	v_mul_f32_e32 v75, v183, v75
	v_mul_f32_e32 v68, v184, v68
	v_mul_f32_e32 v69, v185, v69
	v_mul_f32_e32 v70, v186, v70
	v_mul_f32_e32 v71, v187, v71
	v_mul_f32_e32 v64, v188, v64
	v_mul_f32_e32 v65, v189, v65
	v_mul_f32_e32 v66, v190, v66
	v_mul_f32_e32 v67, v191, v67
	s_waitcnt vmcnt(6)
	v_mul_f32_e32 v158, v214, v68
	v_mul_f32_e32 v159, v215, v69
	v_mul_f32_e32 v160, v216, v70
	v_mul_f32_e32 v161, v217, v71
	v_mul_f32_e32 v162, v218, v64
	v_mul_f32_e32 v163, v219, v65
	v_mul_f32_e32 v164, v220, v66
	v_mul_f32_e32 v165, v221, v67
	v_mul_f32_e32 v246, v222, v68
	v_mul_f32_e32 v247, v223, v69
	v_mul_f32_e32 v248, v224, v70
	v_mul_f32_e32 v249, v225, v71
	v_mul_f32_e32 v250, v226, v64
	v_mul_f32_e32 v251, v227, v65
	v_mul_f32_e32 v192, v228, v66
	v_mul_f32_e32 v128, v229, v67
	v_fma_f32 v158, v222, v76, -v158
	v_fma_f32 v159, v223, v77, -v159
	v_fma_f32 v160, v224, v78, -v160
	v_fma_f32 v161, v225, v79, -v161
	v_fma_f32 v162, v226, v72, -v162
	v_fma_f32 v163, v227, v73, -v163
	v_fma_f32 v164, v228, v74, -v164
	v_fma_f32 v165, v229, v75, -v165
	v_fma_f32 v246, v214, v76, v246
	v_fma_f32 v247, v215, v77, v247
	v_fma_f32 v248, v216, v78, v248
	v_fma_f32 v249, v217, v79, v249
	v_fma_f32 v250, v218, v72, v250
	v_fma_f32 v251, v219, v73, v251
	v_fma_f32 v192, v220, v74, v192
	v_fma_f32 v128, v221, v75, v128
	v_cvt_pk_bf16_f32 v76, v158, v159
	v_cvt_pk_bf16_f32 v77, v160, v161
	v_cvt_pk_bf16_f32 v78, v162, v163
	v_cvt_pk_bf16_f32 v79, v164, v165
	v_cvt_pk_bf16_f32 v72, v246, v247
	v_cvt_pk_bf16_f32 v73, v248, v249
	v_cvt_pk_bf16_f32 v74, v250, v251
	v_cvt_pk_bf16_f32 v75, v192, v128
	s_cbranch_vccz .Lmy_qk_pl3
	global_store_dwordx4 v195, v[76:79], s[54:55] nt
	global_store_dwordx4 v195, v[72:75], s[54:55] offset:64 nt
	s_branch .Lmy_qk_st3
.Lmy_qk_pl3:
	global_store_dwordx4 v195, v[76:79], s[54:55]
	global_store_dwordx4 v195, v[72:75], s[54:55] offset:64
.Lmy_qk_st3:
	s_add_u32 s54, s54, 0x28000
	s_addc_u32 s55, s55, 0
	global_load_dwordx4 v[214:217], v194, s[24:25]
	global_load_dwordx4 v[222:225], v194, s[58:59]
	global_load_dwordx4 v[218:221], v194, s[24:25] offset:16
	global_load_dwordx4 v[226:229], v194, s[58:59] offset:16
	s_add_u32 s24, s24, 0x800
	s_addc_u32 s25, s25, 0
	s_add_u32 s58, s58, 0x800
	s_addc_u32 s59, s59, 0
	v_mul_f32_e32 v60, v60, v240
	v_mul_f32_e32 v61, v61, v240
	v_mul_f32_e32 v62, v62, v240
	v_mul_f32_e32 v63, v63, v240
	v_mul_f32_e32 v56, v56, v240
	v_mul_f32_e32 v57, v57, v240
	v_mul_f32_e32 v58, v58, v240
	v_mul_f32_e32 v59, v59, v240
	v_mul_f32_e32 v52, v52, v240
	v_mul_f32_e32 v53, v53, v240
	v_mul_f32_e32 v54, v54, v240
	v_mul_f32_e32 v55, v55, v240
	v_mul_f32_e32 v48, v48, v240
	v_mul_f32_e32 v49, v49, v240
	v_mul_f32_e32 v50, v50, v240
	v_mul_f32_e32 v51, v51, v240
	v_mul_f32_e32 v60, v176, v60
	v_mul_f32_e32 v61, v177, v61
	v_mul_f32_e32 v62, v178, v62
	v_mul_f32_e32 v63, v179, v63
	v_mul_f32_e32 v56, v180, v56
	v_mul_f32_e32 v57, v181, v57
	v_mul_f32_e32 v58, v182, v58
	v_mul_f32_e32 v59, v183, v59
	v_mul_f32_e32 v52, v184, v52
	v_mul_f32_e32 v53, v185, v53
	v_mul_f32_e32 v54, v186, v54
	v_mul_f32_e32 v55, v187, v55
	v_mul_f32_e32 v48, v188, v48
	v_mul_f32_e32 v49, v189, v49
	v_mul_f32_e32 v50, v190, v50
	v_mul_f32_e32 v51, v191, v51
	s_waitcnt vmcnt(6)
	v_mul_f32_e32 v158, v198, v52
	v_mul_f32_e32 v159, v199, v53
	v_mul_f32_e32 v160, v200, v54
	v_mul_f32_e32 v161, v201, v55
	v_mul_f32_e32 v162, v202, v48
	v_mul_f32_e32 v163, v203, v49
	v_mul_f32_e32 v164, v204, v50
	v_mul_f32_e32 v165, v205, v51
	v_mul_f32_e32 v246, v206, v52
	v_mul_f32_e32 v247, v207, v53
	v_mul_f32_e32 v248, v208, v54
	v_mul_f32_e32 v249, v209, v55
	v_mul_f32_e32 v250, v210, v48
	v_mul_f32_e32 v251, v211, v49
	v_mul_f32_e32 v192, v212, v50
	v_mul_f32_e32 v128, v213, v51
	v_fma_f32 v158, v206, v60, -v158
	v_fma_f32 v159, v207, v61, -v159
	v_fma_f32 v160, v208, v62, -v160
	v_fma_f32 v161, v209, v63, -v161
	v_fma_f32 v162, v210, v56, -v162
	v_fma_f32 v163, v211, v57, -v163
	v_fma_f32 v164, v212, v58, -v164
	v_fma_f32 v165, v213, v59, -v165
	v_fma_f32 v246, v198, v60, v246
	v_fma_f32 v247, v199, v61, v247
	v_fma_f32 v248, v200, v62, v248
	v_fma_f32 v249, v201, v63, v249
	v_fma_f32 v250, v202, v56, v250
	v_fma_f32 v251, v203, v57, v251
	v_fma_f32 v192, v204, v58, v192
	v_fma_f32 v128, v205, v59, v128
	v_cvt_pk_bf16_f32 v60, v158, v159
	v_cvt_pk_bf16_f32 v61, v160, v161
	v_cvt_pk_bf16_f32 v62, v162, v163
	v_cvt_pk_bf16_f32 v63, v164, v165
	v_cvt_pk_bf16_f32 v56, v246, v247
	v_cvt_pk_bf16_f32 v57, v248, v249
	v_cvt_pk_bf16_f32 v58, v250, v251
	v_cvt_pk_bf16_f32 v59, v192, v128
	s_cbranch_vccz .Lmy_qk_pl4
	global_store_dwordx4 v195, v[60:63], s[54:55] nt
	global_store_dwordx4 v195, v[56:59], s[54:55] offset:64 nt
	s_branch .Lmy_qk_st4
.Lmy_qk_pl4:
	global_store_dwordx4 v195, v[60:63], s[54:55]
	global_store_dwordx4 v195, v[56:59], s[54:55] offset:64
.Lmy_qk_st4:
	s_add_u32 s54, s54, 0x8000
	s_addc_u32 s55, s55, 0
	global_load_dwordx4 v[198:201], v194, s[24:25]
	global_load_dwordx4 v[206:209], v194, s[58:59]
	global_load_dwordx4 v[202:205], v194, s[24:25] offset:16
	global_load_dwordx4 v[210:213], v194, s[58:59] offset:16
	s_add_u32 s24, s24, 0x800
	s_addc_u32 s25, s25, 0
	s_add_u32 s58, s58, 0x800
	s_addc_u32 s59, s59, 0
	v_mul_f32_e32 v44, v44, v241
	v_mul_f32_e32 v45, v45, v241
	v_mul_f32_e32 v46, v46, v241
	v_mul_f32_e32 v47, v47, v241
	v_mul_f32_e32 v40, v40, v241
	v_mul_f32_e32 v41, v41, v241
	v_mul_f32_e32 v42, v42, v241
	v_mul_f32_e32 v43, v43, v241
	v_mul_f32_e32 v36, v36, v241
	v_mul_f32_e32 v37, v37, v241
	v_mul_f32_e32 v38, v38, v241
	v_mul_f32_e32 v39, v39, v241
	v_mul_f32_e32 v32, v32, v241
	v_mul_f32_e32 v33, v33, v241
	v_mul_f32_e32 v34, v34, v241
	v_mul_f32_e32 v35, v35, v241
	v_mul_f32_e32 v44, v176, v44
	v_mul_f32_e32 v45, v177, v45
	v_mul_f32_e32 v46, v178, v46
	v_mul_f32_e32 v47, v179, v47
	v_mul_f32_e32 v40, v180, v40
	v_mul_f32_e32 v41, v181, v41
	v_mul_f32_e32 v42, v182, v42
	v_mul_f32_e32 v43, v183, v43
	v_mul_f32_e32 v36, v184, v36
	v_mul_f32_e32 v37, v185, v37
	v_mul_f32_e32 v38, v186, v38
	v_mul_f32_e32 v39, v187, v39
	v_mul_f32_e32 v32, v188, v32
	v_mul_f32_e32 v33, v189, v33
	v_mul_f32_e32 v34, v190, v34
	v_mul_f32_e32 v35, v191, v35
	s_waitcnt vmcnt(6)
	v_mul_f32_e32 v158, v214, v36
	v_mul_f32_e32 v159, v215, v37
	v_mul_f32_e32 v160, v216, v38
	v_mul_f32_e32 v161, v217, v39
	v_mul_f32_e32 v162, v218, v32
	v_mul_f32_e32 v163, v219, v33
	v_mul_f32_e32 v164, v220, v34
	v_mul_f32_e32 v165, v221, v35
	v_mul_f32_e32 v246, v222, v36
	v_mul_f32_e32 v247, v223, v37
	v_mul_f32_e32 v248, v224, v38
	v_mul_f32_e32 v249, v225, v39
	v_mul_f32_e32 v250, v226, v32
	v_mul_f32_e32 v251, v227, v33
	v_mul_f32_e32 v192, v228, v34
	v_mul_f32_e32 v128, v229, v35
	v_fma_f32 v158, v222, v44, -v158
	v_fma_f32 v159, v223, v45, -v159
	v_fma_f32 v160, v224, v46, -v160
	v_fma_f32 v161, v225, v47, -v161
	v_fma_f32 v162, v226, v40, -v162
	v_fma_f32 v163, v227, v41, -v163
	v_fma_f32 v164, v228, v42, -v164
	v_fma_f32 v165, v229, v43, -v165
	v_fma_f32 v246, v214, v44, v246
	v_fma_f32 v247, v215, v45, v247
	v_fma_f32 v248, v216, v46, v248
	v_fma_f32 v249, v217, v47, v249
	v_fma_f32 v250, v218, v40, v250
	v_fma_f32 v251, v219, v41, v251
	v_fma_f32 v192, v220, v42, v192
	v_fma_f32 v128, v221, v43, v128
	v_cvt_pk_bf16_f32 v44, v158, v159
	v_cvt_pk_bf16_f32 v45, v160, v161
	v_cvt_pk_bf16_f32 v46, v162, v163
	v_cvt_pk_bf16_f32 v47, v164, v165
	v_cvt_pk_bf16_f32 v40, v246, v247
	v_cvt_pk_bf16_f32 v41, v248, v249
	v_cvt_pk_bf16_f32 v42, v250, v251
	v_cvt_pk_bf16_f32 v43, v192, v128
	s_cbranch_vccz .Lmy_qk_pl5
	global_store_dwordx4 v195, v[44:47], s[54:55] nt
	global_store_dwordx4 v195, v[40:43], s[54:55] offset:64 nt
	s_branch .Lmy_qk_st5
.Lmy_qk_pl5:
	global_store_dwordx4 v195, v[44:47], s[54:55]
	global_store_dwordx4 v195, v[40:43], s[54:55] offset:64
.Lmy_qk_st5:
	s_add_u32 s54, s54, 0x8000
	s_addc_u32 s55, s55, 0
	global_load_dwordx4 v[214:217], v194, s[24:25]
	global_load_dwordx4 v[222:225], v194, s[58:59]
	global_load_dwordx4 v[218:221], v194, s[24:25] offset:16
	global_load_dwordx4 v[226:229], v194, s[58:59] offset:16
	v_mul_f32_e32 v28, v28, v242
	v_mul_f32_e32 v29, v29, v242
	v_mul_f32_e32 v30, v30, v242
	v_mul_f32_e32 v31, v31, v242
	v_mul_f32_e32 v24, v24, v242
	v_mul_f32_e32 v25, v25, v242
	v_mul_f32_e32 v26, v26, v242
	v_mul_f32_e32 v27, v27, v242
	v_mul_f32_e32 v20, v20, v242
	v_mul_f32_e32 v21, v21, v242
	v_mul_f32_e32 v22, v22, v242
	v_mul_f32_e32 v23, v23, v242
	v_mul_f32_e32 v16, v16, v242
	v_mul_f32_e32 v17, v17, v242
	v_mul_f32_e32 v18, v18, v242
	v_mul_f32_e32 v19, v19, v242
	v_mul_f32_e32 v28, v176, v28
	v_mul_f32_e32 v29, v177, v29
	v_mul_f32_e32 v30, v178, v30
	v_mul_f32_e32 v31, v179, v31
	v_mul_f32_e32 v24, v180, v24
	v_mul_f32_e32 v25, v181, v25
	v_mul_f32_e32 v26, v182, v26
	v_mul_f32_e32 v27, v183, v27
	v_mul_f32_e32 v20, v184, v20
	v_mul_f32_e32 v21, v185, v21
	v_mul_f32_e32 v22, v186, v22
	v_mul_f32_e32 v23, v187, v23
	v_mul_f32_e32 v16, v188, v16
	v_mul_f32_e32 v17, v189, v17
	v_mul_f32_e32 v18, v190, v18
	v_mul_f32_e32 v19, v191, v19
	s_waitcnt vmcnt(6)
	v_mul_f32_e32 v158, v198, v20
	v_mul_f32_e32 v159, v199, v21
	v_mul_f32_e32 v160, v200, v22
	v_mul_f32_e32 v161, v201, v23
	v_mul_f32_e32 v162, v202, v16
	v_mul_f32_e32 v163, v203, v17
	v_mul_f32_e32 v164, v204, v18
	v_mul_f32_e32 v165, v205, v19
	v_mul_f32_e32 v246, v206, v20
	v_mul_f32_e32 v247, v207, v21
	v_mul_f32_e32 v248, v208, v22
	v_mul_f32_e32 v249, v209, v23
	v_mul_f32_e32 v250, v210, v16
	v_mul_f32_e32 v251, v211, v17
	v_mul_f32_e32 v192, v212, v18
	v_mul_f32_e32 v128, v213, v19
	v_fma_f32 v158, v206, v28, -v158
	v_fma_f32 v159, v207, v29, -v159
	v_fma_f32 v160, v208, v30, -v160
	v_fma_f32 v161, v209, v31, -v161
	v_fma_f32 v162, v210, v24, -v162
	v_fma_f32 v163, v211, v25, -v163
	v_fma_f32 v164, v212, v26, -v164
	v_fma_f32 v165, v213, v27, -v165
	v_fma_f32 v246, v198, v28, v246
	v_fma_f32 v247, v199, v29, v247
	v_fma_f32 v248, v200, v30, v248
	v_fma_f32 v249, v201, v31, v249
	v_fma_f32 v250, v202, v24, v250
	v_fma_f32 v251, v203, v25, v251
	v_fma_f32 v192, v204, v26, v192
	v_fma_f32 v128, v205, v27, v128
	v_cvt_pk_bf16_f32 v28, v158, v159
	v_cvt_pk_bf16_f32 v29, v160, v161
	v_cvt_pk_bf16_f32 v30, v162, v163
	v_cvt_pk_bf16_f32 v31, v164, v165
	v_cvt_pk_bf16_f32 v24, v246, v247
	v_cvt_pk_bf16_f32 v25, v248, v249
	v_cvt_pk_bf16_f32 v26, v250, v251
	v_cvt_pk_bf16_f32 v27, v192, v128
	s_cbranch_vccz .Lmy_qk_pl6
	global_store_dwordx4 v195, v[28:31], s[54:55] nt
	global_store_dwordx4 v195, v[24:27], s[54:55] offset:64 nt
	s_branch .Lmy_qk_st6
.Lmy_qk_pl6:
	global_store_dwordx4 v195, v[28:31], s[54:55]
	global_store_dwordx4 v195, v[24:27], s[54:55] offset:64
.Lmy_qk_st6:
	s_add_u32 s54, s54, 0x8000
	s_addc_u32 s55, s55, 0
	v_mul_f32_e32 v12, v12, v243
	v_mul_f32_e32 v13, v13, v243
	v_mul_f32_e32 v14, v14, v243
	v_mul_f32_e32 v15, v15, v243
	v_mul_f32_e32 v8, v8, v243
	v_mul_f32_e32 v9, v9, v243
	v_mul_f32_e32 v10, v10, v243
	v_mul_f32_e32 v11, v11, v243
	v_mul_f32_e32 v4, v4, v243
	v_mul_f32_e32 v5, v5, v243
	v_mul_f32_e32 v6, v6, v243
	v_mul_f32_e32 v7, v7, v243
	v_mul_f32_e32 v0, v0, v243
	v_mul_f32_e32 v1, v1, v243
	v_mul_f32_e32 v2, v2, v243
	v_mul_f32_e32 v3, v3, v243
	v_mul_f32_e32 v12, v176, v12
	v_mul_f32_e32 v13, v177, v13
	v_mul_f32_e32 v14, v178, v14
	v_mul_f32_e32 v15, v179, v15
	v_mul_f32_e32 v8, v180, v8
	v_mul_f32_e32 v9, v181, v9
	v_mul_f32_e32 v10, v182, v10
	v_mul_f32_e32 v11, v183, v11
	v_mul_f32_e32 v4, v184, v4
	v_mul_f32_e32 v5, v185, v5
	v_mul_f32_e32 v6, v186, v6
	v_mul_f32_e32 v7, v187, v7
	v_mul_f32_e32 v0, v188, v0
	v_mul_f32_e32 v1, v189, v1
	v_mul_f32_e32 v2, v190, v2
	v_mul_f32_e32 v3, v191, v3
	s_waitcnt vmcnt(2)
	v_mul_f32_e32 v158, v214, v4
	v_mul_f32_e32 v159, v215, v5
	v_mul_f32_e32 v160, v216, v6
	v_mul_f32_e32 v161, v217, v7
	v_mul_f32_e32 v162, v218, v0
	v_mul_f32_e32 v163, v219, v1
	v_mul_f32_e32 v164, v220, v2
	v_mul_f32_e32 v165, v221, v3
	v_mul_f32_e32 v246, v222, v4
	v_mul_f32_e32 v247, v223, v5
	v_mul_f32_e32 v248, v224, v6
	v_mul_f32_e32 v249, v225, v7
	v_mul_f32_e32 v250, v226, v0
	v_mul_f32_e32 v251, v227, v1
	v_mul_f32_e32 v192, v228, v2
	v_mul_f32_e32 v128, v229, v3
	v_fma_f32 v158, v222, v12, -v158
	v_fma_f32 v159, v223, v13, -v159
	v_fma_f32 v160, v224, v14, -v160
	v_fma_f32 v161, v225, v15, -v161
	v_fma_f32 v162, v226, v8, -v162
	v_fma_f32 v163, v227, v9, -v163
	v_fma_f32 v164, v228, v10, -v164
	v_fma_f32 v165, v229, v11, -v165
	v_fma_f32 v246, v214, v12, v246
	v_fma_f32 v247, v215, v13, v247
	v_fma_f32 v248, v216, v14, v248
	v_fma_f32 v249, v217, v15, v249
	v_fma_f32 v250, v218, v8, v250
	v_fma_f32 v251, v219, v9, v251
	v_fma_f32 v192, v220, v10, v192
	v_fma_f32 v128, v221, v11, v128
	v_cvt_pk_bf16_f32 v12, v158, v159
	v_cvt_pk_bf16_f32 v13, v160, v161
	v_cvt_pk_bf16_f32 v14, v162, v163
	v_cvt_pk_bf16_f32 v15, v164, v165
	v_cvt_pk_bf16_f32 v8, v246, v247
	v_cvt_pk_bf16_f32 v9, v248, v249
	v_cvt_pk_bf16_f32 v10, v250, v251
	v_cvt_pk_bf16_f32 v11, v192, v128
	s_cbranch_vccz .Lmy_qk_pl7
	global_store_dwordx4 v195, v[12:15], s[54:55] nt
	global_store_dwordx4 v195, v[8:11], s[54:55] offset:64 nt
	s_branch .Lmy_qk_st7
.Lmy_qk_pl7:
	global_store_dwordx4 v195, v[12:15], s[54:55]
	global_store_dwordx4 v195, v[8:11], s[54:55] offset:64
.Lmy_qk_st7:
	s_branch .LBB0_561
